# LDS-DMA attention: lag waves pick the counted-wait mode before their MFMA half; dead per-tile address update removed
# baseline (speedup 1.0000x reference)
.Latt_a_stg:
.Latt_a_bar:
	s_cmp_eq_u32 s29, 0
	s_cbranch_scc1 .Lw0_a
	s_waitcnt vmcnt(4) lgkmcnt(0)
	s_barrier
	s_branch .Lwd_a

.Lwd_a:
	s_add_i32 s4, s65, 1
	s_cmp_ge_u32 s4, s66
	s_cbranch_scc1 .Latt_a_nod
	s_add_i32 s4, s65, 2
	s_cmp_ge_u32 s4, s66
	s_cbranch_scc1 .Latt_a_nok
	s_add_i32 m0, s5, s32
	s_nop 0
	global_load_lds_dwordx4 v128, s[80:81]
	s_add_i32 m0, m0, 0x2000
	s_nop 0
	global_load_lds_dwordx4 v129, s[80:81]
	s_cmp_eq_u32 s56, 0
	s_cbranch_scc0 .Ldk_a
	s_add_i32 m0, s5, 0x4000
	s_nop 0
	global_load_lds_dwordx4 v132, s[80:81]

.LBB0_241:
	s_add_i32 s4, s69, 1
	s_cmp_lg_u32 s69, 2
	s_cselect_b32 s4, s4, 0
	s_addk_i32 s68, 0x100
	s_add_i32 s65, s65, 1
	s_add_i32 s33, s33, -1
	s_cmp_eq_u32 s21, s68
	s_cbranch_scc1 .LBB0_243
	s_mov_b32 s87, s69
	s_branch .LBB0_228
